# nt hint also on the first read of the f32 inputs in R0
# speedup vs baseline: 1.0379x; 1.0033x over previous
.LBB0_115:
	s_or_b64 exec, exec, s[12:13]
	v_lshl_add_u64 v[56:57], v[60:61], 0, v[32:33]
	global_load_dwordx4 v[72:75], v[56:57], off nt
	global_load_dwordx4 v[76:79], v[56:57], off offset:16 nt
	global_load_dwordx4 v[80:83], v[56:57], off offset:2048 nt
	global_load_dwordx4 v[84:87], v[56:57], off offset:2064 nt
	s_add_i32 s14, s14, 2
	s_cmp_eq_u32 s14, 4
	s_waitcnt vmcnt(3)
	v_mov_b32_e32 v60, v73
	s_waitcnt vmcnt(2)
	v_mov_b32_e32 v61, v77
	v_mov_b32_e32 v56, v72
	v_mov_b32_e32 v57, v76
	s_waitcnt vmcnt(1)
	v_mov_b32_e32 v94, v81
	s_waitcnt vmcnt(0)
	v_mov_b32_e32 v95, v85
	v_pk_mul_f32 v[60:61], v[60:61], v[60:61]
	v_mov_b32_e32 v88, v74
	v_mov_b32_e32 v89, v78
	v_mov_b32_e32 v92, v80
	v_mov_b32_e32 v93, v84
	v_pk_mul_f32 v[94:95], v[94:95], v[94:95]
	v_pk_fma_f32 v[56:57], v[56:57], v[56:57], v[60:61]
	v_mov_b32_e32 v90, v75
	v_mov_b32_e32 v91, v79
	v_mov_b32_e32 v96, v82
	v_mov_b32_e32 v97, v86
	v_pk_fma_f32 v[60:61], v[92:93], v[92:93], v[94:95]
	v_pk_fma_f32 v[56:57], v[88:89], v[88:89], v[56:57]
	v_mov_b32_e32 v98, v83
	v_mov_b32_e32 v99, v87
	v_pk_fma_f32 v[60:61], v[96:97], v[96:97], v[60:61]
	v_pk_fma_f32 v[56:57], v[90:91], v[90:91], v[56:57]
	v_pk_fma_f32 v[60:61], v[98:99], v[98:99], v[60:61]
	v_add_f32_e32 v56, v56, v57
	v_add_f32_e32 v56, v56, v60
	v_add_f32_e32 v56, v56, v61
	ds_bpermute_b32 v57, v62, v56
	s_waitcnt lgkmcnt(0)
	v_add_f32_e32 v56, v56, v57
	ds_bpermute_b32 v57, v63, v56
	s_waitcnt lgkmcnt(0)
	v_add_f32_e32 v56, v56, v57
	ds_bpermute_b32 v57, v64, v56
	s_waitcnt lgkmcnt(0)
	v_add_f32_e32 v56, v56, v57
	ds_bpermute_b32 v57, v65, v56
	s_waitcnt lgkmcnt(0)
	v_add_f32_e32 v56, v56, v57
	ds_bpermute_b32 v57, v66, v56
	s_waitcnt lgkmcnt(0)
	v_add_f32_e32 v60, v56, v57
	ds_bpermute_b32 v61, v67, v60
	v_lshlrev_b64 v[56:57], 11, v[58:59]
	s_waitcnt lgkmcnt(0)
	v_add_f32_e32 v58, v60, v61
	v_fmamk_f32 v58, v58, 0x3a800000, v70
	v_mul_f32_e32 v59, 0x4b800000, v58
	v_cmp_gt_f32_e32 vcc, s10, v58
	v_lshl_add_u64 v[60:61], v[34:35], 0, v[56:57]
	s_nop 0
	v_cndmask_b32_e32 v58, v58, v59, vcc
	v_rsq_f32_e32 v58, v58
	s_nop 0
	v_mul_f32_e32 v56, 0x45800000, v58
	v_cndmask_b32_e32 v56, v58, v56, vcc
	v_pk_mul_f32 v[58:59], v[74:75], v[56:57] op_sel_hi:[1,0]
	v_pk_mul_f32 v[72:73], v[72:73], v[56:57] op_sel_hi:[1,0]
	v_pk_mul_f32 v[74:75], v[78:79], v[56:57] op_sel_hi:[1,0]
	v_pk_mul_f32 v[76:77], v[76:77], v[56:57] op_sel_hi:[1,0]
	v_pk_mul_f32 v[78:79], v[82:83], v[56:57] op_sel_hi:[1,0]
	v_pk_mul_f32 v[80:81], v[80:81], v[56:57] op_sel_hi:[1,0]
	v_pk_mul_f32 v[82:83], v[86:87], v[56:57] op_sel_hi:[1,0]
	v_pk_mul_f32 v[56:57], v[84:85], v[56:57] op_sel_hi:[1,0]
	v_pk_mul_f32 v[72:73], v[4:5], v[72:73]
	v_pk_mul_f32 v[58:59], v[6:7], v[58:59]
	v_pk_mul_f32 v[76:77], v[0:1], v[76:77]
	v_pk_mul_f32 v[74:75], v[2:3], v[74:75]
	v_pk_mul_f32 v[80:81], v[20:21], v[80:81]
	v_pk_mul_f32 v[78:79], v[22:23], v[78:79]
	v_pk_mul_f32 v[56:57], v[16:17], v[56:57]
	v_pk_mul_f32 v[82:83], v[18:19], v[82:83]
	v_pk_fma_f32 v[58:59], v[40:41], v[58:59], v[14:15]
	v_pk_fma_f32 v[72:73], v[42:43], v[72:73], v[12:13]
	v_pk_fma_f32 v[74:75], v[44:45], v[74:75], v[10:11]
	v_pk_fma_f32 v[76:77], v[46:47], v[76:77], v[8:9]
	v_pk_fma_f32 v[78:79], v[48:49], v[78:79], v[30:31]
	v_pk_fma_f32 v[80:81], v[50:51], v[80:81], v[28:29]
	v_pk_fma_f32 v[82:83], v[52:53], v[82:83], v[26:27]
	v_pk_fma_f32 v[84:85], v[54:55], v[56:57], v[24:25]
	v_cvt_pk_bf16_f32 v56, v72, v73
	v_cvt_pk_bf16_f32 v57, v58, v59
	v_cvt_pk_bf16_f32 v58, v76, v77
	v_cvt_pk_bf16_f32 v59, v74, v75
	v_cvt_pk_bf16_f32 v72, v80, v81
	v_cvt_pk_bf16_f32 v73, v78, v79
	v_cvt_pk_bf16_f32 v74, v84, v85
	v_cvt_pk_bf16_f32 v75, v82, v83
	global_store_dwordx4 v[60:61], v[56:59], off sc1
	global_store_dwordx4 v[60:61], v[72:75], off offset:1024 sc1
	s_cbranch_scc1 .LBB0_113
.LBB0_116:
	v_add_u32_e32 v56, s14, v68
	v_cmp_lt_i32_e32 vcc, s3, v56
	s_and_saveexec_b64 s[12:13], vcc
	s_xor_b64 s[12:13], exec, s[12:13]
	v_add_u32_e32 v58, 0xfffff000, v56
	v_mov_b32_e32 v59, v33
	v_lshlrev_b64 v[58:59], 12, v[58:59]
	v_lshl_add_u64 v[58:59], s[38:39], 0, v[58:59]
	v_mov_b32_e32 v57, v33
	s_andn2_saveexec_b64 s[12:13], s[12:13]
	v_ashrrev_i32_e32 v57, 31, v56
	v_lshlrev_b64 v[58:59], 12, v[56:57]
	v_lshl_add_u64 v[58:59], s[36:37], 0, v[58:59]
	s_or_b64 exec, exec, s[12:13]
	v_lshl_add_u64 v[58:59], v[58:59], 0, v[32:33]
	global_load_dwordx4 v[72:75], v[58:59], off nt
	global_load_dwordx4 v[76:79], v[58:59], off offset:16 nt
	global_load_dwordx4 v[80:83], v[58:59], off offset:2048 nt
	global_load_dwordx4 v[84:87], v[58:59], off offset:2064 nt
	s_waitcnt vmcnt(3)
	v_mov_b32_e32 v60, v73
	s_waitcnt vmcnt(2)
	v_mov_b32_e32 v61, v77
	v_mov_b32_e32 v58, v72
	v_mov_b32_e32 v59, v76
	s_waitcnt vmcnt(1)
	v_mov_b32_e32 v94, v81
	s_waitcnt vmcnt(0)
	v_mov_b32_e32 v95, v85
	v_pk_mul_f32 v[60:61], v[60:61], v[60:61]
	v_mov_b32_e32 v88, v74
	v_mov_b32_e32 v89, v78
	v_mov_b32_e32 v92, v80
	v_mov_b32_e32 v93, v84
	v_pk_mul_f32 v[94:95], v[94:95], v[94:95]
	v_pk_fma_f32 v[58:59], v[58:59], v[58:59], v[60:61]
	v_mov_b32_e32 v90, v75
	v_mov_b32_e32 v91, v79
	v_mov_b32_e32 v96, v82
	v_mov_b32_e32 v97, v86
	v_pk_fma_f32 v[60:61], v[92:93], v[92:93], v[94:95]
	v_pk_fma_f32 v[58:59], v[88:89], v[88:89], v[58:59]
	v_mov_b32_e32 v98, v83
	v_mov_b32_e32 v99, v87
	v_pk_fma_f32 v[60:61], v[96:97], v[96:97], v[60:61]
	v_pk_fma_f32 v[58:59], v[90:91], v[90:91], v[58:59]
	v_pk_fma_f32 v[60:61], v[98:99], v[98:99], v[60:61]
	v_add_f32_e32 v58, v58, v59
	v_add_f32_e32 v58, v58, v60
	v_add_f32_e32 v58, v58, v61
	ds_bpermute_b32 v59, v62, v58
	v_lshlrev_b64 v[60:61], 11, v[56:57]
	v_lshl_add_u64 v[60:61], v[34:35], 0, v[60:61]
	s_waitcnt lgkmcnt(0)
	v_add_f32_e32 v58, v58, v59
	ds_bpermute_b32 v59, v63, v58
	s_waitcnt lgkmcnt(0)
	v_add_f32_e32 v58, v58, v59
	ds_bpermute_b32 v59, v64, v58
	s_waitcnt lgkmcnt(0)
	v_add_f32_e32 v58, v58, v59
	ds_bpermute_b32 v59, v65, v58
	s_waitcnt lgkmcnt(0)
	v_add_f32_e32 v58, v58, v59
	ds_bpermute_b32 v59, v66, v58
	s_waitcnt lgkmcnt(0)
	v_add_f32_e32 v58, v58, v59
	ds_bpermute_b32 v59, v67, v58
	s_waitcnt lgkmcnt(0)
	v_add_f32_e32 v58, v58, v59
	v_fmamk_f32 v58, v58, 0x3a800000, v70
	v_mul_f32_e32 v59, 0x4b800000, v58
	v_cmp_gt_f32_e32 vcc, s10, v58
	s_nop 1
	v_cndmask_b32_e32 v58, v58, v59, vcc
	v_rsq_f32_e32 v59, v58
	v_add_u32_e32 v58, 1, v56
	v_mul_f32_e32 v57, 0x45800000, v59
	v_cndmask_b32_e32 v88, v59, v57, vcc
	v_pk_mul_f32 v[74:75], v[74:75], v[88:89] op_sel_hi:[1,0]
	v_pk_mul_f32 v[72:73], v[72:73], v[88:89] op_sel_hi:[1,0]
	v_pk_mul_f32 v[78:79], v[78:79], v[88:89] op_sel_hi:[1,0]
	v_pk_mul_f32 v[76:77], v[76:77], v[88:89] op_sel_hi:[1,0]
	v_pk_mul_f32 v[82:83], v[82:83], v[88:89] op_sel_hi:[1,0]
	v_pk_mul_f32 v[80:81], v[80:81], v[88:89] op_sel_hi:[1,0]
	v_pk_mul_f32 v[86:87], v[86:87], v[88:89] op_sel_hi:[1,0]
	v_pk_mul_f32 v[84:85], v[84:85], v[88:89] op_sel_hi:[1,0]
	v_pk_mul_f32 v[72:73], v[4:5], v[72:73]
	v_pk_mul_f32 v[74:75], v[6:7], v[74:75]
	v_pk_mul_f32 v[76:77], v[0:1], v[76:77]
	v_pk_mul_f32 v[78:79], v[2:3], v[78:79]
	v_pk_mul_f32 v[80:81], v[20:21], v[80:81]
	v_pk_mul_f32 v[82:83], v[22:23], v[82:83]
	v_pk_mul_f32 v[84:85], v[16:17], v[84:85]
	v_pk_mul_f32 v[86:87], v[18:19], v[86:87]
	v_pk_fma_f32 v[74:75], v[40:41], v[74:75], v[14:15]
	v_pk_fma_f32 v[72:73], v[42:43], v[72:73], v[12:13]
	v_pk_fma_f32 v[78:79], v[44:45], v[78:79], v[10:11]
	v_pk_fma_f32 v[76:77], v[46:47], v[76:77], v[8:9]
	v_pk_fma_f32 v[82:83], v[48:49], v[82:83], v[30:31]
	v_pk_fma_f32 v[80:81], v[50:51], v[80:81], v[28:29]
	v_pk_fma_f32 v[86:87], v[52:53], v[86:87], v[26:27]
	v_pk_fma_f32 v[84:85], v[54:55], v[84:85], v[24:25]
	v_cvt_pk_bf16_f32 v72, v72, v73
	v_cvt_pk_bf16_f32 v73, v74, v75
	v_cvt_pk_bf16_f32 v74, v76, v77
	v_cvt_pk_bf16_f32 v75, v78, v79
	v_cmp_lt_i32_e32 vcc, s3, v58
	v_cvt_pk_bf16_f32 v76, v80, v81
	v_cvt_pk_bf16_f32 v77, v82, v83
	v_cvt_pk_bf16_f32 v78, v84, v85
	v_cvt_pk_bf16_f32 v79, v86, v87
	global_store_dwordx4 v[60:61], v[72:75], off sc1
	global_store_dwordx4 v[60:61], v[76:79], off offset:1024 sc1
	s_and_saveexec_b64 s[12:13], vcc
	s_xor_b64 s[12:13], exec, s[12:13]
	v_add_u32_e32 v56, 0xfffff001, v56
	v_mov_b32_e32 v57, v33
	v_lshlrev_b64 v[56:57], 12, v[56:57]
	v_lshl_add_u64 v[60:61], s[38:39], 0, v[56:57]
	v_mov_b32_e32 v59, v33
	s_andn2_saveexec_b64 s[12:13], s[12:13]
	s_cbranch_execz .LBB0_115
	v_ashrrev_i32_e32 v59, 31, v58
	v_lshlrev_b64 v[56:57], 12, v[58:59]
	v_lshl_add_u64 v[60:61], s[36:37], 0, v[56:57]
	s_branch .LBB0_115
